# code placement: the UP / WIN / DN-OUT K-loop heads aligned to 64 bytes
# baseline (speedup 1.0000x reference)
.Lwinskip_7_pl:
	s_setprio 0
	s_barrier
	s_add_i32 s74, s74, 2
	s_add_u32 s72, s72, 0x100
	s_addc_u32 s73, s73, 0
	s_add_u32 s64, s64, 0x100
	s_addc_u32 s65, s65, 0
	.p2align	6

.LBB0_527:
	s_add_u32 s51, s22, 0x100
	s_addc_u32 s52, s23, 0
	s_add_u32 s22, s30, 0x80
	s_addc_u32 s23, s31, 0
	s_mov_b32 s30, 0
	s_waitcnt lgkmcnt(0)
	s_add_i32 s53, s30, 2
	s_add_u32 s54, s22, 0x80
	s_addc_u32 s31, s23, 0
	s_add_i32 s56, 0, 0x10000
	s_cmp_eq_u32 s46, s30
	s_cselect_b32 s31, s1, s31
	s_cselect_b32 s30, s0, s54
	s_cselect_b32 s55, s21, s52
	s_cselect_b32 s54, s20, s51
	s_add_i32 s57, 0, 0x14000
	v_add_u32_e32 v152, s56, v232
	v_add_u32_e32 v168, s57, v232
	ds_read_b128 v[140:143], v152
	ds_read_b128 v[144:147], v152 offset:1024
	ds_read_b128 v[148:151], v152 offset:2048
	ds_read_b128 v[152:155], v152 offset:3072
	ds_read_b128 v[156:159], v168
	ds_read_b128 v[160:163], v168 offset:1024
	ds_read_b128 v[164:167], v168 offset:2048
	ds_read_b128 v[168:171], v168 offset:3072
	s_add_i32 m0, s28, 0xc000
	ds_read_b128 v[172:175], v236
	ds_read_b128 v[176:179], v236 offset:1024
	ds_read_b128 v[180:183], v236 offset:2048
	ds_read_b128 v[184:187], v236 offset:3072
	ds_read_b128 v[188:191], v236 offset:4096
	ds_read_b128 v[192:195], v236 offset:5120
	ds_read_b128 v[208:211], v236 offset:6144
	ds_read_b128 v[212:215], v236 offset:7168
	global_load_lds_dwordx4 v138, s[22:23]
	s_add_i32 m0, s28, 0xe000
	s_nop 0
	global_load_lds_dwordx4 v136, s[22:23]
	s_waitcnt vmcnt(8)
	s_waitcnt lgkmcnt(0)
	s_barrier
	s_setprio 1
	s_waitcnt lgkmcnt(0)
	v_mfma_f32_16x16x32_bf16 v[130:133], v[140:143], v[172:175], 0
	v_mfma_f32_16x16x32_bf16 v[126:129], v[148:151], v[172:175], 0
	v_mfma_f32_16x16x32_bf16 v[114:117], v[140:143], v[180:183], 0
	v_mfma_f32_16x16x32_bf16 v[110:113], v[148:151], v[180:183], 0
	v_mfma_f32_16x16x32_bf16 v[98:101], v[140:143], v[188:191], 0
	v_mfma_f32_16x16x32_bf16 v[90:93], v[148:151], v[188:191], 0
	v_mfma_f32_16x16x32_bf16 v[78:81], v[140:143], v[208:211], 0
	v_mfma_f32_16x16x32_bf16 v[74:77], v[148:151], v[208:211], 0
	v_mfma_f32_16x16x32_bf16 v[130:133], v[144:147], v[176:179], v[130:133]
	v_mfma_f32_16x16x32_bf16 v[126:129], v[152:155], v[176:179], v[126:129]
	v_mfma_f32_16x16x32_bf16 v[114:117], v[144:147], v[184:187], v[114:117]
	v_mfma_f32_16x16x32_bf16 v[110:113], v[152:155], v[184:187], v[110:113]
	v_mfma_f32_16x16x32_bf16 v[98:101], v[144:147], v[192:195], v[98:101]
	v_mfma_f32_16x16x32_bf16 v[90:93], v[152:155], v[192:195], v[90:93]
	v_mfma_f32_16x16x32_bf16 v[78:81], v[144:147], v[212:215], v[78:81]
	v_mfma_f32_16x16x32_bf16 v[74:77], v[152:155], v[212:215], v[74:77]
	s_setprio 0
	s_setprio 1
	v_mfma_f32_16x16x32_bf16 v[122:125], v[156:159], v[172:175], 0
	v_mfma_f32_16x16x32_bf16 v[118:121], v[164:167], v[172:175], 0
	v_mfma_f32_16x16x32_bf16 v[106:109], v[156:159], v[180:183], 0
	v_mfma_f32_16x16x32_bf16 v[102:105], v[164:167], v[180:183], 0
	v_mfma_f32_16x16x32_bf16 v[86:89], v[156:159], v[188:191], 0
	v_mfma_f32_16x16x32_bf16 v[82:85], v[164:167], v[188:191], 0
	v_mfma_f32_16x16x32_bf16 v[70:73], v[156:159], v[208:211], 0
	v_mfma_f32_16x16x32_bf16 v[66:69], v[164:167], v[208:211], 0
	v_mfma_f32_16x16x32_bf16 v[122:125], v[160:163], v[176:179], v[122:125]
	v_mfma_f32_16x16x32_bf16 v[118:121], v[168:171], v[176:179], v[118:121]
	v_mfma_f32_16x16x32_bf16 v[106:109], v[160:163], v[184:187], v[106:109]
	v_mfma_f32_16x16x32_bf16 v[102:105], v[168:171], v[184:187], v[102:105]
	v_mfma_f32_16x16x32_bf16 v[86:89], v[160:163], v[192:195], v[86:89]
	v_mfma_f32_16x16x32_bf16 v[82:85], v[168:171], v[192:195], v[82:85]
	v_mfma_f32_16x16x32_bf16 v[70:73], v[160:163], v[212:215], v[70:73]
	v_mfma_f32_16x16x32_bf16 v[66:69], v[168:171], v[212:215], v[66:69]
	s_setprio 0
	s_barrier
	s_add_i32 s56, s56, s25
	s_mov_b32 m0, s56
	ds_read_b128 v[172:175], v236 offset:16384
	ds_read_b128 v[176:179], v236 offset:17408
	ds_read_b128 v[180:183], v236 offset:18432
	ds_read_b128 v[184:187], v236 offset:19456
	ds_read_b128 v[188:191], v236 offset:20480
	ds_read_b128 v[192:195], v236 offset:21504
	ds_read_b128 v[208:211], v236 offset:22528
	ds_read_b128 v[212:215], v236 offset:23552
	global_load_lds_dwordx4 v0, s[54:55]
	s_add_i32 m0, s56, 0x2000
	s_nop 0
	global_load_lds_dwordx4 v94, s[54:55]
	s_add_u32 s54, s54, s6
	s_addc_u32 s55, s55, 0
	s_add_i32 s56, s57, s25
	s_mov_b32 m0, s56
	s_nop 0
	global_load_lds_dwordx4 v0, s[54:55]
	s_add_i32 m0, s56, 0x2000
	s_nop 0
	global_load_lds_dwordx4 v94, s[54:55]
	s_mov_b32 m0, s28
	s_nop 0
	global_load_lds_dwordx4 v0, s[30:31]
	s_mov_b32 m0, s29
	s_nop 0
	global_load_lds_dwordx4 v94, s[30:31]
	s_waitcnt vmcnt(8)
	s_waitcnt lgkmcnt(0)
	s_barrier
	s_setprio 1
	s_waitcnt lgkmcnt(0)
	v_mfma_f32_16x16x32_bf16 v[62:65], v[140:143], v[172:175], 0
	v_mfma_f32_16x16x32_bf16 v[58:61], v[148:151], v[172:175], 0
	v_mfma_f32_16x16x32_bf16 v[46:49], v[140:143], v[180:183], 0
	v_mfma_f32_16x16x32_bf16 v[42:45], v[148:151], v[180:183], 0
	v_mfma_f32_16x16x32_bf16 v[30:33], v[140:143], v[188:191], 0
	v_mfma_f32_16x16x32_bf16 v[26:29], v[148:151], v[188:191], 0
	v_mfma_f32_16x16x32_bf16 v[14:17], v[140:143], v[208:211], 0
	v_mfma_f32_16x16x32_bf16 v[10:13], v[148:151], v[208:211], 0
	v_mfma_f32_16x16x32_bf16 v[62:65], v[144:147], v[176:179], v[62:65]
	v_mfma_f32_16x16x32_bf16 v[58:61], v[152:155], v[176:179], v[58:61]
	v_mfma_f32_16x16x32_bf16 v[46:49], v[144:147], v[184:187], v[46:49]
	v_mfma_f32_16x16x32_bf16 v[42:45], v[152:155], v[184:187], v[42:45]
	v_mfma_f32_16x16x32_bf16 v[30:33], v[144:147], v[192:195], v[30:33]
	v_mfma_f32_16x16x32_bf16 v[26:29], v[152:155], v[192:195], v[26:29]
	v_mfma_f32_16x16x32_bf16 v[14:17], v[144:147], v[212:215], v[14:17]
	v_mfma_f32_16x16x32_bf16 v[10:13], v[152:155], v[212:215], v[10:13]
	s_setprio 0
	s_setprio 1
	v_mfma_f32_16x16x32_bf16 v[54:57], v[156:159], v[172:175], 0
	v_mfma_f32_16x16x32_bf16 v[50:53], v[164:167], v[172:175], 0
	v_mfma_f32_16x16x32_bf16 v[38:41], v[156:159], v[180:183], 0
	v_mfma_f32_16x16x32_bf16 v[34:37], v[164:167], v[180:183], 0
	v_mfma_f32_16x16x32_bf16 v[22:25], v[156:159], v[188:191], 0
	v_mfma_f32_16x16x32_bf16 v[18:21], v[164:167], v[188:191], 0
	v_mfma_f32_16x16x32_bf16 v[6:9], v[156:159], v[208:211], 0
	v_mfma_f32_16x16x32_bf16 v[2:5], v[164:167], v[208:211], 0
	v_mfma_f32_16x16x32_bf16 v[54:57], v[160:163], v[176:179], v[54:57]
	v_mfma_f32_16x16x32_bf16 v[50:53], v[168:171], v[176:179], v[50:53]
	v_mfma_f32_16x16x32_bf16 v[38:41], v[160:163], v[184:187], v[38:41]
	v_mfma_f32_16x16x32_bf16 v[34:37], v[168:171], v[184:187], v[34:37]
	v_mfma_f32_16x16x32_bf16 v[22:25], v[160:163], v[192:195], v[22:25]
	v_mfma_f32_16x16x32_bf16 v[18:21], v[168:171], v[192:195], v[18:21]
	v_mfma_f32_16x16x32_bf16 v[6:9], v[160:163], v[212:215], v[6:9]
	v_mfma_f32_16x16x32_bf16 v[2:5], v[168:171], v[212:215], v[2:5]
	s_setprio 0
	s_barrier
	s_add_i32 s56, 0, 0x18000
	s_add_i32 s57, 0, 0x1c000
	v_add_u32_e32 v152, s56, v232
	v_add_u32_e32 v168, s57, v232
	ds_read_b128 v[140:143], v152
	ds_read_b128 v[144:147], v152 offset:1024
	ds_read_b128 v[148:151], v152 offset:2048
	ds_read_b128 v[152:155], v152 offset:3072
	ds_read_b128 v[156:159], v168
	ds_read_b128 v[160:163], v168 offset:1024
	ds_read_b128 v[164:167], v168 offset:2048
	ds_read_b128 v[168:171], v168 offset:3072
	s_add_u32 s30, s30, s6
	s_addc_u32 s31, s31, 0
	s_mov_b32 m0, s33
	ds_read_b128 v[172:175], v236 offset:32768
	ds_read_b128 v[176:179], v236 offset:33792
	ds_read_b128 v[180:183], v236 offset:34816
	ds_read_b128 v[184:187], v236 offset:35840
	ds_read_b128 v[188:191], v236 offset:36864
	ds_read_b128 v[192:195], v236 offset:37888
	ds_read_b128 v[208:211], v236 offset:38912
	ds_read_b128 v[212:215], v236 offset:39936
	global_load_lds_dwordx4 v0, s[30:31]
	s_mov_b32 m0, s42
	s_nop 0
	global_load_lds_dwordx4 v94, s[30:31]
	s_waitcnt vmcnt(8)
	s_waitcnt lgkmcnt(0)
	s_barrier
	s_setprio 1
	s_waitcnt lgkmcnt(0)
	v_mfma_f32_16x16x32_bf16 v[130:133], v[140:143], v[172:175], v[130:133]
	v_mfma_f32_16x16x32_bf16 v[126:129], v[148:151], v[172:175], v[126:129]
	v_mfma_f32_16x16x32_bf16 v[114:117], v[140:143], v[180:183], v[114:117]
	v_mfma_f32_16x16x32_bf16 v[110:113], v[148:151], v[180:183], v[110:113]
	v_mfma_f32_16x16x32_bf16 v[98:101], v[140:143], v[188:191], v[98:101]
	v_mfma_f32_16x16x32_bf16 v[90:93], v[148:151], v[188:191], v[90:93]
	v_mfma_f32_16x16x32_bf16 v[78:81], v[140:143], v[208:211], v[78:81]
	v_mfma_f32_16x16x32_bf16 v[74:77], v[148:151], v[208:211], v[74:77]
	v_mfma_f32_16x16x32_bf16 v[130:133], v[144:147], v[176:179], v[130:133]
	v_mfma_f32_16x16x32_bf16 v[126:129], v[152:155], v[176:179], v[126:129]
	v_mfma_f32_16x16x32_bf16 v[114:117], v[144:147], v[184:187], v[114:117]
	v_mfma_f32_16x16x32_bf16 v[110:113], v[152:155], v[184:187], v[110:113]
	v_mfma_f32_16x16x32_bf16 v[98:101], v[144:147], v[192:195], v[98:101]
	v_mfma_f32_16x16x32_bf16 v[90:93], v[152:155], v[192:195], v[90:93]
	v_mfma_f32_16x16x32_bf16 v[78:81], v[144:147], v[212:215], v[78:81]
	v_mfma_f32_16x16x32_bf16 v[74:77], v[152:155], v[212:215], v[74:77]
	s_setprio 0
	s_setprio 1
	v_mfma_f32_16x16x32_bf16 v[122:125], v[156:159], v[172:175], v[122:125]
	v_mfma_f32_16x16x32_bf16 v[118:121], v[164:167], v[172:175], v[118:121]
	v_mfma_f32_16x16x32_bf16 v[106:109], v[156:159], v[180:183], v[106:109]
	v_mfma_f32_16x16x32_bf16 v[102:105], v[164:167], v[180:183], v[102:105]
	v_mfma_f32_16x16x32_bf16 v[86:89], v[156:159], v[188:191], v[86:89]
	v_mfma_f32_16x16x32_bf16 v[82:85], v[164:167], v[188:191], v[82:85]
	v_mfma_f32_16x16x32_bf16 v[70:73], v[156:159], v[208:211], v[70:73]
	v_mfma_f32_16x16x32_bf16 v[66:69], v[164:167], v[208:211], v[66:69]
	v_mfma_f32_16x16x32_bf16 v[122:125], v[160:163], v[176:179], v[122:125]
	v_mfma_f32_16x16x32_bf16 v[118:121], v[168:171], v[176:179], v[118:121]
	v_mfma_f32_16x16x32_bf16 v[106:109], v[160:163], v[184:187], v[106:109]
	v_mfma_f32_16x16x32_bf16 v[102:105], v[168:171], v[184:187], v[102:105]
	v_mfma_f32_16x16x32_bf16 v[86:89], v[160:163], v[192:195], v[86:89]
	v_mfma_f32_16x16x32_bf16 v[82:85], v[168:171], v[192:195], v[82:85]
	v_mfma_f32_16x16x32_bf16 v[70:73], v[160:163], v[212:215], v[70:73]
	v_mfma_f32_16x16x32_bf16 v[66:69], v[168:171], v[212:215], v[66:69]
	s_setprio 0
	s_barrier
	s_add_i32 s71, s56, s25
	s_sub_u32 s54, s54, s6
	s_subb_u32 s55, s55, 0
	s_add_u32 s54, s54, 0x80
	s_addc_u32 s55, s55, 0
	s_mov_b32 m0, s71
	ds_read_b128 v[172:175], v236 offset:49152
	ds_read_b128 v[176:179], v236 offset:50176
	ds_read_b128 v[180:183], v236 offset:51200
	ds_read_b128 v[184:187], v236 offset:52224
	ds_read_b128 v[188:191], v236 offset:53248
	ds_read_b128 v[192:195], v236 offset:54272
	ds_read_b128 v[208:211], v236 offset:55296
	ds_read_b128 v[212:215], v236 offset:56320
	global_load_lds_dwordx4 v0, s[54:55]
	s_add_i32 m0, s71, 0x2000
	s_nop 0
	global_load_lds_dwordx4 v94, s[54:55]
	s_add_i32 s71, s57, s25
	s_add_u32 s54, s54, s6
	s_addc_u32 s55, s55, 0
	s_mov_b32 m0, s71
	s_nop 0
	global_load_lds_dwordx4 v0, s[54:55]
	s_add_i32 m0, s71, 0x2000
	s_nop 0
	global_load_lds_dwordx4 v94, s[54:55]
	s_sub_u32 s30, s30, s6
	s_subb_u32 s31, s31, 0
	s_add_u32 s30, s30, 0x80
	s_addc_u32 s31, s31, 0
	s_mov_b32 m0, s43
	s_nop 0
	global_load_lds_dwordx4 v0, s[30:31]
	s_mov_b32 m0, s44
	s_nop 0
	global_load_lds_dwordx4 v94, s[30:31]
	s_waitcnt vmcnt(8)
	s_waitcnt lgkmcnt(0)
	s_barrier
	s_setprio 1
	s_waitcnt lgkmcnt(0)
	v_mfma_f32_16x16x32_bf16 v[62:65], v[140:143], v[172:175], v[62:65]
	v_mfma_f32_16x16x32_bf16 v[58:61], v[148:151], v[172:175], v[58:61]
	v_mfma_f32_16x16x32_bf16 v[46:49], v[140:143], v[180:183], v[46:49]
	v_mfma_f32_16x16x32_bf16 v[42:45], v[148:151], v[180:183], v[42:45]
	v_mfma_f32_16x16x32_bf16 v[30:33], v[140:143], v[188:191], v[30:33]
	v_mfma_f32_16x16x32_bf16 v[26:29], v[148:151], v[188:191], v[26:29]
	v_mfma_f32_16x16x32_bf16 v[14:17], v[140:143], v[208:211], v[14:17]
	v_mfma_f32_16x16x32_bf16 v[10:13], v[148:151], v[208:211], v[10:13]
	v_mfma_f32_16x16x32_bf16 v[62:65], v[144:147], v[176:179], v[62:65]
	v_mfma_f32_16x16x32_bf16 v[58:61], v[152:155], v[176:179], v[58:61]
	v_mfma_f32_16x16x32_bf16 v[46:49], v[144:147], v[184:187], v[46:49]
	v_mfma_f32_16x16x32_bf16 v[42:45], v[152:155], v[184:187], v[42:45]
	v_mfma_f32_16x16x32_bf16 v[30:33], v[144:147], v[192:195], v[30:33]
	v_mfma_f32_16x16x32_bf16 v[26:29], v[152:155], v[192:195], v[26:29]
	v_mfma_f32_16x16x32_bf16 v[14:17], v[144:147], v[212:215], v[14:17]
	v_mfma_f32_16x16x32_bf16 v[10:13], v[152:155], v[212:215], v[10:13]
	s_setprio 0
	s_setprio 1
	v_mfma_f32_16x16x32_bf16 v[54:57], v[156:159], v[172:175], v[54:57]
	v_mfma_f32_16x16x32_bf16 v[50:53], v[164:167], v[172:175], v[50:53]
	v_mfma_f32_16x16x32_bf16 v[38:41], v[156:159], v[180:183], v[38:41]
	v_mfma_f32_16x16x32_bf16 v[34:37], v[164:167], v[180:183], v[34:37]
	v_mfma_f32_16x16x32_bf16 v[22:25], v[156:159], v[188:191], v[22:25]
	v_mfma_f32_16x16x32_bf16 v[18:21], v[164:167], v[188:191], v[18:21]
	v_mfma_f32_16x16x32_bf16 v[6:9], v[156:159], v[208:211], v[6:9]
	v_mfma_f32_16x16x32_bf16 v[2:5], v[164:167], v[208:211], v[2:5]
	v_mfma_f32_16x16x32_bf16 v[54:57], v[160:163], v[176:179], v[54:57]
	v_mfma_f32_16x16x32_bf16 v[50:53], v[168:171], v[176:179], v[50:53]
	v_mfma_f32_16x16x32_bf16 v[38:41], v[160:163], v[184:187], v[38:41]
	v_mfma_f32_16x16x32_bf16 v[34:37], v[168:171], v[184:187], v[34:37]
	v_mfma_f32_16x16x32_bf16 v[22:25], v[160:163], v[192:195], v[22:25]
	v_mfma_f32_16x16x32_bf16 v[18:21], v[168:171], v[192:195], v[18:21]
	v_mfma_f32_16x16x32_bf16 v[6:9], v[160:163], v[212:215], v[6:9]
	v_mfma_f32_16x16x32_bf16 v[2:5], v[168:171], v[212:215], v[2:5]
	s_setprio 0
	s_barrier
	s_add_u32 s51, s51, 0x100
	s_addc_u32 s52, s52, 0
	s_add_u32 s22, s22, 0x100
	s_addc_u32 s23, s23, 0
	s_mov_b32 s30, s53
	.p2align	6

.LBB0_564:
	s_ashr_i32 s21, s20, 31
	s_lshl_b64 s[22:23], s[20:21], 19
	s_add_u32 s22, s14, s22
	s_addc_u32 s23, s15, s23
	s_and_b64 s[30:31], s[36:37], exec
	s_cselect_b32 s21, s23, s41
	s_cselect_b32 s47, s22, s40
	s_ashr_i32 s19, s18, 31
	s_lshl_b64 s[30:31], s[18:19], 19
	s_add_u32 s30, s2, s30
	s_addc_u32 s31, s3, s31
	s_and_b64 s[42:43], s[36:37], exec
	s_cselect_b32 s19, s31, s39
	s_cselect_b32 s48, s30, s38
	s_add_u32 s49, s38, 0x100
	s_addc_u32 s50, s39, 0
	s_add_u32 s38, s40, 0x40080
	s_addc_u32 s39, s41, 0
	s_mov_b32 s51, -2
	s_add_u32 s40, s38, 0xfffc0080
	s_addc_u32 s41, s39, -1
	s_add_i32 s52, 0, 0x10000
	s_cmp_eq_u32 s51, 12
	s_cselect_b32 s43, s21, s41
	s_cselect_b32 s42, s47, s40
	v_add_u32_e32 v0, s52, v141
	s_cselect_b32 s41, s19, s50
	s_cselect_b32 s40, s48, s49
	s_add_i32 s54, 0, 0x14000
	ds_read_b128 v[146:149], v0
	ds_read_b128 v[150:153], v0 offset:1024
	ds_read_b128 v[154:157], v0 offset:2048
	ds_read_b128 v[158:161], v0 offset:3072
	v_add_u32_e32 v0, s54, v141
	ds_read_b128 v[162:165], v0
	ds_read_b128 v[166:169], v0 offset:1024
	ds_read_b128 v[170:173], v0 offset:2048
	ds_read_b128 v[174:177], v0 offset:3072
	s_add_i32 m0, s8, 0xc000
	ds_read_b128 v[178:181], v145
	ds_read_b128 v[182:185], v145 offset:1024
	ds_read_b128 v[186:189], v145 offset:2048
	ds_read_b128 v[190:193], v145 offset:3072
	ds_read_b128 v[194:197], v145 offset:4096
	ds_read_b128 v[208:211], v145 offset:5120
	ds_read_b128 v[212:215], v145 offset:6144
	ds_read_b128 v[216:219], v145 offset:7168
	global_load_lds_dwordx4 v138, s[38:39]
	s_add_i32 m0, s8, 0xe000
	s_nop 0
	global_load_lds_dwordx4 v136, s[38:39]
	s_waitcnt vmcnt(8)
	s_waitcnt lgkmcnt(0)
	s_barrier
	s_setprio 1
	s_waitcnt lgkmcnt(0)
	v_mfma_f32_16x16x32_bf16 v[130:133], v[146:149], v[178:181], 0
	v_mfma_f32_16x16x32_bf16 v[126:129], v[154:157], v[178:181], 0
	v_mfma_f32_16x16x32_bf16 v[114:117], v[146:149], v[186:189], 0
	v_mfma_f32_16x16x32_bf16 v[110:113], v[154:157], v[186:189], 0
	v_mfma_f32_16x16x32_bf16 v[98:101], v[146:149], v[194:197], 0
	v_mfma_f32_16x16x32_bf16 v[90:93], v[154:157], v[194:197], 0
	v_mfma_f32_16x16x32_bf16 v[78:81], v[146:149], v[212:215], 0
	v_mfma_f32_16x16x32_bf16 v[74:77], v[154:157], v[212:215], 0
	v_mfma_f32_16x16x32_bf16 v[130:133], v[150:153], v[182:185], v[130:133]
	v_mfma_f32_16x16x32_bf16 v[126:129], v[158:161], v[182:185], v[126:129]
	v_mfma_f32_16x16x32_bf16 v[114:117], v[150:153], v[190:193], v[114:117]
	v_mfma_f32_16x16x32_bf16 v[110:113], v[158:161], v[190:193], v[110:113]
	v_mfma_f32_16x16x32_bf16 v[98:101], v[150:153], v[208:211], v[98:101]
	v_mfma_f32_16x16x32_bf16 v[90:93], v[158:161], v[208:211], v[90:93]
	v_mfma_f32_16x16x32_bf16 v[78:81], v[150:153], v[216:219], v[78:81]
	v_mfma_f32_16x16x32_bf16 v[74:77], v[158:161], v[216:219], v[74:77]
	s_setprio 0
	s_setprio 1
	v_mfma_f32_16x16x32_bf16 v[122:125], v[162:165], v[178:181], 0
	v_mfma_f32_16x16x32_bf16 v[118:121], v[170:173], v[178:181], 0
	v_mfma_f32_16x16x32_bf16 v[106:109], v[162:165], v[186:189], 0
	v_mfma_f32_16x16x32_bf16 v[102:105], v[170:173], v[186:189], 0
	v_mfma_f32_16x16x32_bf16 v[86:89], v[162:165], v[194:197], 0
	v_mfma_f32_16x16x32_bf16 v[82:85], v[170:173], v[194:197], 0
	v_mfma_f32_16x16x32_bf16 v[70:73], v[162:165], v[212:215], 0
	v_mfma_f32_16x16x32_bf16 v[66:69], v[170:173], v[212:215], 0
	v_mfma_f32_16x16x32_bf16 v[122:125], v[166:169], v[182:185], v[122:125]
	v_mfma_f32_16x16x32_bf16 v[118:121], v[174:177], v[182:185], v[118:121]
	v_mfma_f32_16x16x32_bf16 v[106:109], v[166:169], v[190:193], v[106:109]
	v_mfma_f32_16x16x32_bf16 v[102:105], v[174:177], v[190:193], v[102:105]
	v_mfma_f32_16x16x32_bf16 v[86:89], v[166:169], v[208:211], v[86:89]
	v_mfma_f32_16x16x32_bf16 v[82:85], v[174:177], v[208:211], v[82:85]
	v_mfma_f32_16x16x32_bf16 v[70:73], v[166:169], v[216:219], v[70:73]
	v_mfma_f32_16x16x32_bf16 v[66:69], v[174:177], v[216:219], v[66:69]
	s_setprio 0
	s_barrier
	s_add_i32 s52, s52, s6
	s_mov_b32 m0, s52
	ds_read_b128 v[178:181], v145 offset:16384
	ds_read_b128 v[182:185], v145 offset:17408
	ds_read_b128 v[186:189], v145 offset:18432
	ds_read_b128 v[190:193], v145 offset:19456
	ds_read_b128 v[194:197], v145 offset:20480
	ds_read_b128 v[208:211], v145 offset:21504
	ds_read_b128 v[212:215], v145 offset:22528
	ds_read_b128 v[216:219], v145 offset:23552
	global_load_lds_dwordx4 v134, s[40:41]
	s_add_i32 m0, s52, 0x2000
	s_add_u32 s52, s40, 0x40000
	s_addc_u32 s53, s41, 0
	s_add_i32 s54, s54, s6
	global_load_lds_dwordx4 v94, s[40:41]
	s_mov_b32 m0, s54
	s_nop 0
	global_load_lds_dwordx4 v134, s[52:53]
	s_add_i32 m0, s54, 0x2000
	s_nop 0
	global_load_lds_dwordx4 v94, s[52:53]
	s_mov_b32 m0, s8
	s_nop 0
	global_load_lds_dwordx4 v134, s[42:43]
	s_mov_b32 m0, s9
	s_nop 0
	global_load_lds_dwordx4 v94, s[42:43]
	s_waitcnt vmcnt(8)
	s_waitcnt lgkmcnt(0)
	s_barrier
	s_setprio 1
	s_waitcnt lgkmcnt(0)
	v_mfma_f32_16x16x32_bf16 v[62:65], v[146:149], v[178:181], 0
	v_mfma_f32_16x16x32_bf16 v[58:61], v[154:157], v[178:181], 0
	v_mfma_f32_16x16x32_bf16 v[46:49], v[146:149], v[186:189], 0
	v_mfma_f32_16x16x32_bf16 v[42:45], v[154:157], v[186:189], 0
	v_mfma_f32_16x16x32_bf16 v[30:33], v[146:149], v[194:197], 0
	v_mfma_f32_16x16x32_bf16 v[26:29], v[154:157], v[194:197], 0
	v_mfma_f32_16x16x32_bf16 v[14:17], v[146:149], v[212:215], 0
	v_mfma_f32_16x16x32_bf16 v[10:13], v[154:157], v[212:215], 0
	v_mfma_f32_16x16x32_bf16 v[62:65], v[150:153], v[182:185], v[62:65]
	v_mfma_f32_16x16x32_bf16 v[58:61], v[158:161], v[182:185], v[58:61]
	v_mfma_f32_16x16x32_bf16 v[46:49], v[150:153], v[190:193], v[46:49]
	v_mfma_f32_16x16x32_bf16 v[42:45], v[158:161], v[190:193], v[42:45]
	v_mfma_f32_16x16x32_bf16 v[30:33], v[150:153], v[208:211], v[30:33]
	v_mfma_f32_16x16x32_bf16 v[26:29], v[158:161], v[208:211], v[26:29]
	v_mfma_f32_16x16x32_bf16 v[14:17], v[150:153], v[216:219], v[14:17]
	v_mfma_f32_16x16x32_bf16 v[10:13], v[158:161], v[216:219], v[10:13]
	s_setprio 0
	s_setprio 1
	v_mfma_f32_16x16x32_bf16 v[54:57], v[162:165], v[178:181], 0
	v_mfma_f32_16x16x32_bf16 v[50:53], v[170:173], v[178:181], 0
	v_mfma_f32_16x16x32_bf16 v[38:41], v[162:165], v[186:189], 0
	v_mfma_f32_16x16x32_bf16 v[34:37], v[170:173], v[186:189], 0
	v_mfma_f32_16x16x32_bf16 v[22:25], v[162:165], v[194:197], 0
	v_mfma_f32_16x16x32_bf16 v[18:21], v[170:173], v[194:197], 0
	v_mfma_f32_16x16x32_bf16 v[6:9], v[162:165], v[212:215], 0
	v_mfma_f32_16x16x32_bf16 v[2:5], v[170:173], v[212:215], 0
	v_mfma_f32_16x16x32_bf16 v[54:57], v[166:169], v[182:185], v[54:57]
	v_mfma_f32_16x16x32_bf16 v[50:53], v[174:177], v[182:185], v[50:53]
	v_mfma_f32_16x16x32_bf16 v[38:41], v[166:169], v[190:193], v[38:41]
	v_mfma_f32_16x16x32_bf16 v[34:37], v[174:177], v[190:193], v[34:37]
	v_mfma_f32_16x16x32_bf16 v[22:25], v[166:169], v[208:211], v[22:25]
	v_mfma_f32_16x16x32_bf16 v[18:21], v[174:177], v[208:211], v[18:21]
	v_mfma_f32_16x16x32_bf16 v[6:9], v[166:169], v[216:219], v[6:9]
	v_mfma_f32_16x16x32_bf16 v[2:5], v[174:177], v[216:219], v[2:5]
	s_setprio 0
	s_barrier
	s_add_i32 s52, 0, 0x18000
	v_add_u32_e32 v0, s52, v141
	s_add_i32 s53, 0, 0x1c000
	ds_read_b128 v[146:149], v0
	ds_read_b128 v[150:153], v0 offset:1024
	ds_read_b128 v[154:157], v0 offset:2048
	ds_read_b128 v[158:161], v0 offset:3072
	v_add_u32_e32 v0, s53, v141
	ds_read_b128 v[162:165], v0
	ds_read_b128 v[166:169], v0 offset:1024
	ds_read_b128 v[170:173], v0 offset:2048
	ds_read_b128 v[174:177], v0 offset:3072
	s_add_u32 s42, s42, 0x40000
	s_addc_u32 s43, s43, 0
	s_mov_b32 m0, s12
	ds_read_b128 v[178:181], v145 offset:32768
	ds_read_b128 v[182:185], v145 offset:33792
	ds_read_b128 v[186:189], v145 offset:34816
	ds_read_b128 v[190:193], v145 offset:35840
	ds_read_b128 v[194:197], v145 offset:36864
	ds_read_b128 v[208:211], v145 offset:37888
	ds_read_b128 v[212:215], v145 offset:38912
	ds_read_b128 v[216:219], v145 offset:39936
	global_load_lds_dwordx4 v134, s[42:43]
	s_mov_b32 m0, s13
	s_nop 0
	global_load_lds_dwordx4 v94, s[42:43]
	s_waitcnt vmcnt(8)
	s_waitcnt lgkmcnt(0)
	s_barrier
	s_setprio 1
	s_waitcnt lgkmcnt(0)
	v_mfma_f32_16x16x32_bf16 v[130:133], v[146:149], v[178:181], v[130:133]
	v_mfma_f32_16x16x32_bf16 v[126:129], v[154:157], v[178:181], v[126:129]
	v_mfma_f32_16x16x32_bf16 v[114:117], v[146:149], v[186:189], v[114:117]
	v_mfma_f32_16x16x32_bf16 v[110:113], v[154:157], v[186:189], v[110:113]
	v_mfma_f32_16x16x32_bf16 v[98:101], v[146:149], v[194:197], v[98:101]
	v_mfma_f32_16x16x32_bf16 v[90:93], v[154:157], v[194:197], v[90:93]
	v_mfma_f32_16x16x32_bf16 v[78:81], v[146:149], v[212:215], v[78:81]
	v_mfma_f32_16x16x32_bf16 v[74:77], v[154:157], v[212:215], v[74:77]
	v_mfma_f32_16x16x32_bf16 v[130:133], v[150:153], v[182:185], v[130:133]
	v_mfma_f32_16x16x32_bf16 v[126:129], v[158:161], v[182:185], v[126:129]
	v_mfma_f32_16x16x32_bf16 v[114:117], v[150:153], v[190:193], v[114:117]
	v_mfma_f32_16x16x32_bf16 v[110:113], v[158:161], v[190:193], v[110:113]
	v_mfma_f32_16x16x32_bf16 v[98:101], v[150:153], v[208:211], v[98:101]
	v_mfma_f32_16x16x32_bf16 v[90:93], v[158:161], v[208:211], v[90:93]
	v_mfma_f32_16x16x32_bf16 v[78:81], v[150:153], v[216:219], v[78:81]
	v_mfma_f32_16x16x32_bf16 v[74:77], v[158:161], v[216:219], v[74:77]
	s_setprio 0
	s_setprio 1
	v_mfma_f32_16x16x32_bf16 v[122:125], v[162:165], v[178:181], v[122:125]
	v_mfma_f32_16x16x32_bf16 v[118:121], v[170:173], v[178:181], v[118:121]
	v_mfma_f32_16x16x32_bf16 v[106:109], v[162:165], v[186:189], v[106:109]
	v_mfma_f32_16x16x32_bf16 v[102:105], v[170:173], v[186:189], v[102:105]
	v_mfma_f32_16x16x32_bf16 v[86:89], v[162:165], v[194:197], v[86:89]
	v_mfma_f32_16x16x32_bf16 v[82:85], v[170:173], v[194:197], v[82:85]
	v_mfma_f32_16x16x32_bf16 v[70:73], v[162:165], v[212:215], v[70:73]
	v_mfma_f32_16x16x32_bf16 v[66:69], v[170:173], v[212:215], v[66:69]
	v_mfma_f32_16x16x32_bf16 v[122:125], v[166:169], v[182:185], v[122:125]
	v_mfma_f32_16x16x32_bf16 v[118:121], v[174:177], v[182:185], v[118:121]
	v_mfma_f32_16x16x32_bf16 v[106:109], v[166:169], v[190:193], v[106:109]
	v_mfma_f32_16x16x32_bf16 v[102:105], v[174:177], v[190:193], v[102:105]
	v_mfma_f32_16x16x32_bf16 v[86:89], v[166:169], v[208:211], v[86:89]
	v_mfma_f32_16x16x32_bf16 v[82:85], v[174:177], v[208:211], v[82:85]
	v_mfma_f32_16x16x32_bf16 v[70:73], v[166:169], v[216:219], v[70:73]
	v_mfma_f32_16x16x32_bf16 v[66:69], v[174:177], v[216:219], v[66:69]
	s_setprio 0
	s_barrier
	s_add_i32 s54, s52, s6
	s_add_i32 m0, s54, 0xffffff80
	ds_read_b128 v[178:181], v145 offset:49152
	ds_read_b128 v[182:185], v145 offset:50176
	ds_read_b128 v[186:189], v145 offset:51200
	ds_read_b128 v[190:193], v145 offset:52224
	ds_read_b128 v[194:197], v145 offset:53248
	ds_read_b128 v[208:211], v145 offset:54272
	ds_read_b128 v[212:215], v145 offset:55296
	ds_read_b128 v[216:219], v145 offset:56320
	global_load_lds_dwordx4 v134, s[40:41] offset:128
	s_add_i32 m0, s54, 0x1f80
	s_nop 0
	global_load_lds_dwordx4 v94, s[40:41] offset:128
	s_add_i32 s54, s53, s6
	s_add_u32 s40, s40, 0x40080
	s_addc_u32 s41, s41, 0
	s_mov_b32 m0, s54
	s_nop 0
	global_load_lds_dwordx4 v134, s[40:41]
	s_add_i32 m0, s54, 0x2000
	s_nop 0
	global_load_lds_dwordx4 v94, s[40:41]
	s_add_u32 s42, s42, 0xfffc0080
	s_addc_u32 s43, s43, -1
	s_mov_b32 m0, s28
	s_nop 0
	global_load_lds_dwordx4 v134, s[42:43]
	s_mov_b32 m0, s29
	s_nop 0
	global_load_lds_dwordx4 v94, s[42:43]
	s_waitcnt vmcnt(8)
	s_waitcnt lgkmcnt(0)
	s_barrier
	s_setprio 1
	s_waitcnt lgkmcnt(0)
	v_mfma_f32_16x16x32_bf16 v[62:65], v[146:149], v[178:181], v[62:65]
	v_mfma_f32_16x16x32_bf16 v[58:61], v[154:157], v[178:181], v[58:61]
	v_mfma_f32_16x16x32_bf16 v[46:49], v[146:149], v[186:189], v[46:49]
	v_mfma_f32_16x16x32_bf16 v[42:45], v[154:157], v[186:189], v[42:45]
	v_mfma_f32_16x16x32_bf16 v[30:33], v[146:149], v[194:197], v[30:33]
	v_mfma_f32_16x16x32_bf16 v[26:29], v[154:157], v[194:197], v[26:29]
	v_mfma_f32_16x16x32_bf16 v[14:17], v[146:149], v[212:215], v[14:17]
	v_mfma_f32_16x16x32_bf16 v[10:13], v[154:157], v[212:215], v[10:13]
	v_mfma_f32_16x16x32_bf16 v[62:65], v[150:153], v[182:185], v[62:65]
	v_mfma_f32_16x16x32_bf16 v[58:61], v[158:161], v[182:185], v[58:61]
	v_mfma_f32_16x16x32_bf16 v[46:49], v[150:153], v[190:193], v[46:49]
	v_mfma_f32_16x16x32_bf16 v[42:45], v[158:161], v[190:193], v[42:45]
	v_mfma_f32_16x16x32_bf16 v[30:33], v[150:153], v[208:211], v[30:33]
	v_mfma_f32_16x16x32_bf16 v[26:29], v[158:161], v[208:211], v[26:29]
	v_mfma_f32_16x16x32_bf16 v[14:17], v[150:153], v[216:219], v[14:17]
	v_mfma_f32_16x16x32_bf16 v[10:13], v[158:161], v[216:219], v[10:13]
	s_setprio 0
	s_setprio 1
	v_mfma_f32_16x16x32_bf16 v[54:57], v[162:165], v[178:181], v[54:57]
	v_mfma_f32_16x16x32_bf16 v[50:53], v[170:173], v[178:181], v[50:53]
	v_mfma_f32_16x16x32_bf16 v[38:41], v[162:165], v[186:189], v[38:41]
	v_mfma_f32_16x16x32_bf16 v[34:37], v[170:173], v[186:189], v[34:37]
	v_mfma_f32_16x16x32_bf16 v[22:25], v[162:165], v[194:197], v[22:25]
	v_mfma_f32_16x16x32_bf16 v[18:21], v[170:173], v[194:197], v[18:21]
	v_mfma_f32_16x16x32_bf16 v[6:9], v[162:165], v[212:215], v[6:9]
	v_mfma_f32_16x16x32_bf16 v[2:5], v[170:173], v[212:215], v[2:5]
	v_mfma_f32_16x16x32_bf16 v[54:57], v[166:169], v[182:185], v[54:57]
	v_mfma_f32_16x16x32_bf16 v[50:53], v[174:177], v[182:185], v[50:53]
	v_mfma_f32_16x16x32_bf16 v[38:41], v[166:169], v[190:193], v[38:41]
	v_mfma_f32_16x16x32_bf16 v[34:37], v[174:177], v[190:193], v[34:37]
	v_mfma_f32_16x16x32_bf16 v[22:25], v[166:169], v[208:211], v[22:25]
	v_mfma_f32_16x16x32_bf16 v[18:21], v[174:177], v[208:211], v[18:21]
	v_mfma_f32_16x16x32_bf16 v[6:9], v[166:169], v[216:219], v[6:9]
	v_mfma_f32_16x16x32_bf16 v[2:5], v[174:177], v[216:219], v[2:5]
	s_setprio 0
	s_barrier
	s_add_i32 s51, s51, 2
	s_add_u32 s49, s49, 0x100
	s_addc_u32 s50, s50, 0
	s_add_u32 s38, s38, 0x100
	s_addc_u32 s39, s39, 0
	.p2align	6
